# half-tile K-loop copy for the f32-residual GEMM path; no per-iteration skip checks in the main loop
# speedup vs baseline: 1.0069x; 1.0069x over previous
.LBB0_409:
	v_mov_b32_e32 v157, 0
	s_andn2_b64 vcc, exec, s[76:77]
	v_mov_b32_e32 v156, v157
	v_mov_b32_e32 v155, v157
	v_mov_b32_e32 v154, v157
	v_mov_b32_e32 v161, v157
	v_mov_b32_e32 v160, v157
	v_mov_b32_e32 v159, v157
	v_mov_b32_e32 v158, v157
	v_mov_b32_e32 v145, v157
	v_mov_b32_e32 v144, v157
	v_mov_b32_e32 v143, v157
	v_mov_b32_e32 v142, v157
	v_mov_b32_e32 v141, v157
	v_mov_b32_e32 v140, v157
	v_mov_b32_e32 v139, v157
	v_mov_b32_e32 v138, v157
	v_mov_b32_e32 v129, v157
	v_mov_b32_e32 v128, v157
	v_mov_b32_e32 v127, v157
	v_mov_b32_e32 v126, v157
	v_mov_b32_e32 v125, v157
	v_mov_b32_e32 v124, v157
	v_mov_b32_e32 v123, v157
	v_mov_b32_e32 v122, v157
	v_mov_b32_e32 v89, v157
	v_mov_b32_e32 v88, v157
	v_mov_b32_e32 v87, v157
	v_mov_b32_e32 v86, v157
	v_mov_b32_e32 v85, v157
	v_mov_b32_e32 v84, v157
	v_mov_b32_e32 v83, v157
	v_mov_b32_e32 v82, v157
	v_mov_b32_e32 v153, v157
	v_mov_b32_e32 v152, v157
	v_mov_b32_e32 v151, v157
	v_mov_b32_e32 v150, v157
	v_mov_b32_e32 v149, v157
	v_mov_b32_e32 v148, v157
	v_mov_b32_e32 v147, v157
	v_mov_b32_e32 v146, v157
	v_mov_b32_e32 v137, v157
	v_mov_b32_e32 v136, v157
	v_mov_b32_e32 v135, v157
	v_mov_b32_e32 v134, v157
	v_mov_b32_e32 v133, v157
	v_mov_b32_e32 v132, v157
	v_mov_b32_e32 v131, v157
	v_mov_b32_e32 v130, v157
	v_mov_b32_e32 v121, v157
	v_mov_b32_e32 v120, v157
	v_mov_b32_e32 v119, v157
	v_mov_b32_e32 v118, v157
	v_mov_b32_e32 v117, v157
	v_mov_b32_e32 v116, v157
	v_mov_b32_e32 v115, v157
	v_mov_b32_e32 v114, v157
	v_mov_b32_e32 v73, v157
	v_mov_b32_e32 v72, v157
	v_mov_b32_e32 v71, v157
	v_mov_b32_e32 v70, v157
	v_mov_b32_e32 v69, v157
	v_mov_b32_e32 v68, v157
	v_mov_b32_e32 v67, v157
	v_mov_b32_e32 v66, v157
	v_mov_b32_e32 v65, v157
	v_mov_b32_e32 v64, v157
	v_mov_b32_e32 v63, v157
	v_mov_b32_e32 v62, v157
	v_mov_b32_e32 v61, v157
	v_mov_b32_e32 v60, v157
	v_mov_b32_e32 v59, v157
	v_mov_b32_e32 v58, v157
	v_mov_b32_e32 v49, v157
	v_mov_b32_e32 v48, v157
	v_mov_b32_e32 v47, v157
	v_mov_b32_e32 v46, v157
	v_mov_b32_e32 v45, v157
	v_mov_b32_e32 v44, v157
	v_mov_b32_e32 v43, v157
	v_mov_b32_e32 v42, v157
	v_mov_b32_e32 v31, v157
	v_mov_b32_e32 v30, v157
	v_mov_b32_e32 v29, v157
	v_mov_b32_e32 v28, v157
	v_mov_b32_e32 v27, v157
	v_mov_b32_e32 v26, v157
	v_mov_b32_e32 v25, v157
	v_mov_b32_e32 v24, v157
	v_mov_b32_e32 v15, v157
	v_mov_b32_e32 v14, v157
	v_mov_b32_e32 v13, v157
	v_mov_b32_e32 v12, v157
	v_mov_b32_e32 v11, v157
	v_mov_b32_e32 v10, v157
	v_mov_b32_e32 v9, v157
	v_mov_b32_e32 v8, v157
	v_mov_b32_e32 v57, v157
	v_mov_b32_e32 v56, v157
	v_mov_b32_e32 v55, v157
	v_mov_b32_e32 v54, v157
	v_mov_b32_e32 v53, v157
	v_mov_b32_e32 v52, v157
	v_mov_b32_e32 v51, v157
	v_mov_b32_e32 v50, v157
	v_mov_b32_e32 v41, v157
	v_mov_b32_e32 v40, v157
	v_mov_b32_e32 v39, v157
	v_mov_b32_e32 v38, v157
	v_mov_b32_e32 v37, v157
	v_mov_b32_e32 v36, v157
	v_mov_b32_e32 v35, v157
	v_mov_b32_e32 v34, v157
	v_mov_b32_e32 v23, v157
	v_mov_b32_e32 v22, v157
	v_mov_b32_e32 v21, v157
	v_mov_b32_e32 v20, v157
	v_mov_b32_e32 v19, v157
	v_mov_b32_e32 v18, v157
	v_mov_b32_e32 v17, v157
	v_mov_b32_e32 v16, v157
	v_mov_b32_e32 v7, v157
	v_mov_b32_e32 v6, v157
	v_mov_b32_e32 v5, v157
	v_mov_b32_e32 v4, v157
	v_mov_b32_e32 v3, v157
	v_mov_b32_e32 v2, v157
	v_mov_b32_e32 v1, v157
	v_mov_b32_e32 v0, v157
	s_cbranch_vccnz .LBB0_413
	s_add_u32 s42, s84, 0x80
	s_addc_u32 s43, s85, 0
	s_add_u32 s48, s44, 0x100
	s_addc_u32 s49, s45, 0
	s_mov_b32 s44, 0
	s_bitcmp1_b32 s99, 0
	s_cbranch_scc1 .Lhalf_B
.LBB0_411:
	s_add_i32 s84, s44, 2
	s_add_u32 s10, s42, 0x80
	s_addc_u32 s45, s43, 0
	s_add_i32 s52, 0, 0x10000
	s_cmp_eq_u32 s30, s44
	s_cselect_b32 s45, s81, s45
	s_cselect_b32 s44, s80, s10
	v_add_u32_e32 v32, s52, v216
	s_cselect_b32 s91, s83, s49
	s_cselect_b32 s90, s82, s48
	s_add_i32 s10, 0, 0x14000
	ds_read_b128 v[74:77], v32
	ds_read_b128 v[78:81], v32 offset:1024
	ds_read_b128 v[90:93], v32 offset:2048
	ds_read_b128 v[94:97], v32 offset:3072
	v_add_u32_e32 v32, s10, v216
	ds_read_b128 v[98:101], v32
	ds_read_b128 v[102:105], v32 offset:1024
	ds_read_b128 v[106:109], v32 offset:2048
	ds_read_b128 v[110:113], v32 offset:3072
	v_lshl_add_u64 v[188:189], s[42:43], 0, v[176:177]
	s_add_i32 m0, s3, 0xc000
	ds_read_b128 v[162:165], v218
	ds_read_b128 v[180:183], v218 offset:1024
	ds_read_b128 v[184:187], v218 offset:2048
	ds_read_b128 v[224:227], v218 offset:3072
	ds_read_b128 v[228:231], v218 offset:4096
	ds_read_b128 v[232:235], v218 offset:5120
	ds_read_b128 v[236:239], v218 offset:6144
	ds_read_b128 v[240:243], v218 offset:7168
	global_load_lds_dwordx4 v[188:189], off
	v_lshl_add_u64 v[188:189], s[42:43], 0, v[178:179]
	s_add_i32 m0, s3, 0xe000
	s_nop 0
	global_load_lds_dwordx4 v[188:189], off
	s_waitcnt vmcnt(8)
	s_waitcnt lgkmcnt(0)
	s_barrier
	s_setprio 1
	s_waitcnt lgkmcnt(0)
	v_mfma_f32_16x16x32_bf16 v[154:157], v[74:77], v[162:165], v[154:157]
	v_mfma_f32_16x16x32_bf16 v[158:161], v[90:93], v[162:165], v[158:161]
	v_mfma_f32_16x16x32_bf16 v[142:145], v[74:77], v[184:187], v[142:145]
	v_mfma_f32_16x16x32_bf16 v[138:141], v[90:93], v[184:187], v[138:141]
	v_mfma_f32_16x16x32_bf16 v[126:129], v[74:77], v[228:231], v[126:129]
	v_mfma_f32_16x16x32_bf16 v[122:125], v[90:93], v[228:231], v[122:125]
	v_mfma_f32_16x16x32_bf16 v[86:89], v[74:77], v[236:239], v[86:89]
	v_mfma_f32_16x16x32_bf16 v[82:85], v[90:93], v[236:239], v[82:85]
	v_mfma_f32_16x16x32_bf16 v[154:157], v[78:81], v[180:183], v[154:157]
	v_mfma_f32_16x16x32_bf16 v[158:161], v[94:97], v[180:183], v[158:161]
	v_mfma_f32_16x16x32_bf16 v[142:145], v[78:81], v[224:227], v[142:145]
	v_mfma_f32_16x16x32_bf16 v[138:141], v[94:97], v[224:227], v[138:141]
	v_mfma_f32_16x16x32_bf16 v[126:129], v[78:81], v[232:235], v[126:129]
	v_mfma_f32_16x16x32_bf16 v[122:125], v[94:97], v[232:235], v[122:125]
	v_mfma_f32_16x16x32_bf16 v[86:89], v[78:81], v[240:243], v[86:89]
	v_mfma_f32_16x16x32_bf16 v[82:85], v[94:97], v[240:243], v[82:85]
	s_setprio 0
	s_setprio 1
	v_mfma_f32_16x16x32_bf16 v[150:153], v[98:101], v[162:165], v[150:153]
	v_mfma_f32_16x16x32_bf16 v[146:149], v[106:109], v[162:165], v[146:149]
	v_mfma_f32_16x16x32_bf16 v[134:137], v[98:101], v[184:187], v[134:137]
	v_mfma_f32_16x16x32_bf16 v[130:133], v[106:109], v[184:187], v[130:133]
	v_mfma_f32_16x16x32_bf16 v[118:121], v[98:101], v[228:231], v[118:121]
	v_mfma_f32_16x16x32_bf16 v[114:117], v[106:109], v[228:231], v[114:117]
	v_mfma_f32_16x16x32_bf16 v[70:73], v[98:101], v[236:239], v[70:73]
	v_mfma_f32_16x16x32_bf16 v[66:69], v[106:109], v[236:239], v[66:69]
	v_mfma_f32_16x16x32_bf16 v[150:153], v[102:105], v[180:183], v[150:153]
	v_mfma_f32_16x16x32_bf16 v[146:149], v[110:113], v[180:183], v[146:149]
	v_mfma_f32_16x16x32_bf16 v[134:137], v[102:105], v[224:227], v[134:137]
	v_mfma_f32_16x16x32_bf16 v[130:133], v[110:113], v[224:227], v[130:133]
	v_mfma_f32_16x16x32_bf16 v[118:121], v[102:105], v[232:235], v[118:121]
	v_mfma_f32_16x16x32_bf16 v[114:117], v[110:113], v[232:235], v[114:117]
	v_mfma_f32_16x16x32_bf16 v[70:73], v[102:105], v[240:243], v[70:73]
	v_mfma_f32_16x16x32_bf16 v[66:69], v[110:113], v[240:243], v[66:69]
	s_setprio 0
	s_barrier
	s_add_i32 s52, s52, s2
	v_lshl_add_u64 v[188:189], s[90:91], 0, v[170:171]
	s_mov_b32 m0, s52
	ds_read_b128 v[162:165], v218 offset:16384
	ds_read_b128 v[180:183], v218 offset:17408
	ds_read_b128 v[184:187], v218 offset:18432
	ds_read_b128 v[224:227], v218 offset:19456
	ds_read_b128 v[228:231], v218 offset:20480
	ds_read_b128 v[232:235], v218 offset:21504
	ds_read_b128 v[236:239], v218 offset:22528
	ds_read_b128 v[240:243], v218 offset:23552
	global_load_lds_dwordx4 v[188:189], off
	s_add_i32 m0, s52, 0x2000
	v_lshl_add_u64 v[202:203], s[90:91], 0, v[174:175]
	s_add_u32 s90, s90, s0
	s_addc_u32 s91, s91, s1
	s_add_i32 s10, s10, s2
	global_load_lds_dwordx4 v[202:203], off
	v_lshl_add_u64 v[204:205], s[90:91], 0, v[170:171]
	s_mov_b32 m0, s10
	v_lshl_add_u64 v[212:213], s[90:91], 0, v[174:175]
	global_load_lds_dwordx4 v[204:205], off
	s_add_i32 m0, s10, 0x2000
	v_lshl_add_u64 v[244:245], s[44:45], 0, v[168:169]
	global_load_lds_dwordx4 v[212:213], off
	s_mov_b32 m0, s3
	v_lshl_add_u64 v[246:247], s[44:45], 0, v[172:173]
	global_load_lds_dwordx4 v[244:245], off
	s_mov_b32 m0, s7
	s_nop 0
	global_load_lds_dwordx4 v[246:247], off
	s_waitcnt vmcnt(8)
	s_waitcnt lgkmcnt(0)
	s_barrier
	s_setprio 1
	s_waitcnt lgkmcnt(0)
	v_mfma_f32_16x16x32_bf16 v[62:65], v[74:77], v[162:165], v[62:65]
	v_mfma_f32_16x16x32_bf16 v[58:61], v[90:93], v[162:165], v[58:61]
	v_mfma_f32_16x16x32_bf16 v[46:49], v[74:77], v[184:187], v[46:49]
	v_mfma_f32_16x16x32_bf16 v[42:45], v[90:93], v[184:187], v[42:45]
	v_mfma_f32_16x16x32_bf16 v[28:31], v[74:77], v[228:231], v[28:31]
	v_mfma_f32_16x16x32_bf16 v[24:27], v[90:93], v[228:231], v[24:27]
	v_mfma_f32_16x16x32_bf16 v[12:15], v[74:77], v[236:239], v[12:15]
	v_mfma_f32_16x16x32_bf16 v[8:11], v[90:93], v[236:239], v[8:11]
	v_mfma_f32_16x16x32_bf16 v[62:65], v[78:81], v[180:183], v[62:65]
	v_mfma_f32_16x16x32_bf16 v[58:61], v[94:97], v[180:183], v[58:61]
	v_mfma_f32_16x16x32_bf16 v[46:49], v[78:81], v[224:227], v[46:49]
	v_mfma_f32_16x16x32_bf16 v[42:45], v[94:97], v[224:227], v[42:45]
	v_mfma_f32_16x16x32_bf16 v[28:31], v[78:81], v[232:235], v[28:31]
	v_mfma_f32_16x16x32_bf16 v[24:27], v[94:97], v[232:235], v[24:27]
	v_mfma_f32_16x16x32_bf16 v[12:15], v[78:81], v[240:243], v[12:15]
	v_mfma_f32_16x16x32_bf16 v[8:11], v[94:97], v[240:243], v[8:11]
	s_setprio 0
	s_setprio 1
	v_mfma_f32_16x16x32_bf16 v[54:57], v[98:101], v[162:165], v[54:57]
	v_mfma_f32_16x16x32_bf16 v[50:53], v[106:109], v[162:165], v[50:53]
	v_mfma_f32_16x16x32_bf16 v[38:41], v[98:101], v[184:187], v[38:41]
	v_mfma_f32_16x16x32_bf16 v[34:37], v[106:109], v[184:187], v[34:37]
	v_mfma_f32_16x16x32_bf16 v[20:23], v[98:101], v[228:231], v[20:23]
	v_mfma_f32_16x16x32_bf16 v[16:19], v[106:109], v[228:231], v[16:19]
	v_mfma_f32_16x16x32_bf16 v[4:7], v[98:101], v[236:239], v[4:7]
	v_mfma_f32_16x16x32_bf16 v[0:3], v[106:109], v[236:239], v[0:3]
	v_mfma_f32_16x16x32_bf16 v[54:57], v[102:105], v[180:183], v[54:57]
	v_mfma_f32_16x16x32_bf16 v[50:53], v[110:113], v[180:183], v[50:53]
	v_mfma_f32_16x16x32_bf16 v[38:41], v[102:105], v[224:227], v[38:41]
	v_mfma_f32_16x16x32_bf16 v[34:37], v[110:113], v[224:227], v[34:37]
	v_mfma_f32_16x16x32_bf16 v[20:23], v[102:105], v[232:235], v[20:23]
	v_mfma_f32_16x16x32_bf16 v[16:19], v[110:113], v[232:235], v[16:19]
	v_mfma_f32_16x16x32_bf16 v[4:7], v[102:105], v[240:243], v[4:7]
	v_mfma_f32_16x16x32_bf16 v[0:3], v[110:113], v[240:243], v[0:3]
	s_setprio 0
	s_barrier
	s_add_i32 s10, 0, 0x18000
	v_add_u32_e32 v32, s10, v216
	s_add_i32 s52, 0, 0x1c000
	ds_read_b128 v[74:77], v32
	ds_read_b128 v[78:81], v32 offset:1024
	ds_read_b128 v[90:93], v32 offset:2048
	ds_read_b128 v[94:97], v32 offset:3072
	v_add_u32_e32 v32, s52, v216
	ds_read_b128 v[98:101], v32
	ds_read_b128 v[102:105], v32 offset:1024
	ds_read_b128 v[106:109], v32 offset:2048
	ds_read_b128 v[110:113], v32 offset:3072
	s_add_u32 s44, s44, s0
	s_addc_u32 s45, s45, s1
	s_mov_b32 m0, s9
	v_lshl_add_u64 v[248:249], s[44:45], 0, v[168:169]
	ds_read_b128 v[162:165], v218 offset:32768
	ds_read_b128 v[180:183], v218 offset:33792
	ds_read_b128 v[184:187], v218 offset:34816
	ds_read_b128 v[224:227], v218 offset:35840
	ds_read_b128 v[228:231], v218 offset:36864
	ds_read_b128 v[232:235], v218 offset:37888
	ds_read_b128 v[236:239], v218 offset:38912
	ds_read_b128 v[240:243], v218 offset:39936
	global_load_lds_dwordx4 v[248:249], off
	v_lshl_add_u64 v[248:249], s[44:45], 0, v[172:173]
	s_mov_b32 m0, s12
	s_nop 0
	global_load_lds_dwordx4 v[248:249], off
	s_waitcnt vmcnt(8)
	s_waitcnt lgkmcnt(0)
	s_barrier
	s_setprio 1
	s_waitcnt lgkmcnt(0)
	v_mfma_f32_16x16x32_bf16 v[154:157], v[74:77], v[162:165], v[154:157]
	v_mfma_f32_16x16x32_bf16 v[158:161], v[90:93], v[162:165], v[158:161]
	v_mfma_f32_16x16x32_bf16 v[142:145], v[74:77], v[184:187], v[142:145]
	v_mfma_f32_16x16x32_bf16 v[138:141], v[90:93], v[184:187], v[138:141]
	v_mfma_f32_16x16x32_bf16 v[126:129], v[74:77], v[228:231], v[126:129]
	v_mfma_f32_16x16x32_bf16 v[122:125], v[90:93], v[228:231], v[122:125]
	v_mfma_f32_16x16x32_bf16 v[86:89], v[74:77], v[236:239], v[86:89]
	v_mfma_f32_16x16x32_bf16 v[82:85], v[90:93], v[236:239], v[82:85]
	v_mfma_f32_16x16x32_bf16 v[154:157], v[78:81], v[180:183], v[154:157]
	v_mfma_f32_16x16x32_bf16 v[158:161], v[94:97], v[180:183], v[158:161]
	v_mfma_f32_16x16x32_bf16 v[142:145], v[78:81], v[224:227], v[142:145]
	v_mfma_f32_16x16x32_bf16 v[138:141], v[94:97], v[224:227], v[138:141]
	v_mfma_f32_16x16x32_bf16 v[126:129], v[78:81], v[232:235], v[126:129]
	v_mfma_f32_16x16x32_bf16 v[122:125], v[94:97], v[232:235], v[122:125]
	v_mfma_f32_16x16x32_bf16 v[86:89], v[78:81], v[240:243], v[86:89]
	v_mfma_f32_16x16x32_bf16 v[82:85], v[94:97], v[240:243], v[82:85]
	s_setprio 0
	s_setprio 1
	v_mfma_f32_16x16x32_bf16 v[150:153], v[98:101], v[162:165], v[150:153]
	v_mfma_f32_16x16x32_bf16 v[146:149], v[106:109], v[162:165], v[146:149]
	v_mfma_f32_16x16x32_bf16 v[134:137], v[98:101], v[184:187], v[134:137]
	v_mfma_f32_16x16x32_bf16 v[130:133], v[106:109], v[184:187], v[130:133]
	v_mfma_f32_16x16x32_bf16 v[118:121], v[98:101], v[228:231], v[118:121]
	v_mfma_f32_16x16x32_bf16 v[114:117], v[106:109], v[228:231], v[114:117]
	v_mfma_f32_16x16x32_bf16 v[70:73], v[98:101], v[236:239], v[70:73]
	v_mfma_f32_16x16x32_bf16 v[66:69], v[106:109], v[236:239], v[66:69]
	v_mfma_f32_16x16x32_bf16 v[150:153], v[102:105], v[180:183], v[150:153]
	v_mfma_f32_16x16x32_bf16 v[146:149], v[110:113], v[180:183], v[146:149]
	v_mfma_f32_16x16x32_bf16 v[134:137], v[102:105], v[224:227], v[134:137]
	v_mfma_f32_16x16x32_bf16 v[130:133], v[110:113], v[224:227], v[130:133]
	v_mfma_f32_16x16x32_bf16 v[118:121], v[102:105], v[232:235], v[118:121]
	v_mfma_f32_16x16x32_bf16 v[114:117], v[110:113], v[232:235], v[114:117]
	v_mfma_f32_16x16x32_bf16 v[70:73], v[102:105], v[240:243], v[70:73]
	v_mfma_f32_16x16x32_bf16 v[66:69], v[110:113], v[240:243], v[66:69]
	s_setprio 0
	s_barrier
	s_add_i32 s10, s10, s2
	v_lshl_add_u64 v[188:189], v[188:189], 0, s[56:57]
	s_mov_b32 m0, s10
	ds_read_b128 v[162:165], v218 offset:49152
	ds_read_b128 v[180:183], v218 offset:50176
	ds_read_b128 v[184:187], v218 offset:51200
	ds_read_b128 v[224:227], v218 offset:52224
	ds_read_b128 v[228:231], v218 offset:53248
	ds_read_b128 v[232:235], v218 offset:54272
	ds_read_b128 v[236:239], v218 offset:55296
	ds_read_b128 v[240:243], v218 offset:56320
	global_load_lds_dwordx4 v[188:189], off
	v_lshl_add_u64 v[188:189], v[202:203], 0, s[56:57]
	s_add_i32 m0, s10, 0x2000
	s_add_i32 s10, s52, s2
	global_load_lds_dwordx4 v[188:189], off
	v_lshl_add_u64 v[188:189], v[204:205], 0, s[56:57]
	s_mov_b32 m0, s10
	s_nop 0
	global_load_lds_dwordx4 v[188:189], off
	v_lshl_add_u64 v[188:189], v[212:213], 0, s[56:57]
	s_add_i32 m0, s10, 0x2000
	s_nop 0
	global_load_lds_dwordx4 v[188:189], off
	v_lshl_add_u64 v[188:189], v[244:245], 0, s[56:57]
	s_mov_b32 m0, s13
	s_nop 0
	global_load_lds_dwordx4 v[188:189], off
	v_lshl_add_u64 v[188:189], v[246:247], 0, s[56:57]
	s_mov_b32 m0, s17
	s_nop 0
	global_load_lds_dwordx4 v[188:189], off
	s_waitcnt vmcnt(8)
	s_waitcnt lgkmcnt(0)
	s_barrier
	s_setprio 1
	s_waitcnt lgkmcnt(0)
	s_nop 0
	v_mfma_f32_16x16x32_bf16 v[62:65], v[74:77], v[162:165], v[62:65]
	v_mfma_f32_16x16x32_bf16 v[58:61], v[90:93], v[162:165], v[58:61]
	v_mfma_f32_16x16x32_bf16 v[46:49], v[74:77], v[184:187], v[46:49]
	v_mfma_f32_16x16x32_bf16 v[42:45], v[90:93], v[184:187], v[42:45]
	v_mfma_f32_16x16x32_bf16 v[28:31], v[74:77], v[228:231], v[28:31]
	v_mfma_f32_16x16x32_bf16 v[24:27], v[90:93], v[228:231], v[24:27]
	v_mfma_f32_16x16x32_bf16 v[12:15], v[74:77], v[236:239], v[12:15]
	v_mfma_f32_16x16x32_bf16 v[8:11], v[90:93], v[236:239], v[8:11]
	v_mfma_f32_16x16x32_bf16 v[62:65], v[78:81], v[180:183], v[62:65]
	v_mfma_f32_16x16x32_bf16 v[58:61], v[94:97], v[180:183], v[58:61]
	v_mfma_f32_16x16x32_bf16 v[46:49], v[78:81], v[224:227], v[46:49]
	v_mfma_f32_16x16x32_bf16 v[42:45], v[94:97], v[224:227], v[42:45]
	v_mfma_f32_16x16x32_bf16 v[28:31], v[78:81], v[232:235], v[28:31]
	v_mfma_f32_16x16x32_bf16 v[24:27], v[94:97], v[232:235], v[24:27]
	v_mfma_f32_16x16x32_bf16 v[12:15], v[78:81], v[240:243], v[12:15]
	v_mfma_f32_16x16x32_bf16 v[8:11], v[94:97], v[240:243], v[8:11]
	s_setprio 0
	s_setprio 1
	v_mfma_f32_16x16x32_bf16 v[54:57], v[98:101], v[162:165], v[54:57]
	v_mfma_f32_16x16x32_bf16 v[50:53], v[106:109], v[162:165], v[50:53]
	v_mfma_f32_16x16x32_bf16 v[38:41], v[98:101], v[184:187], v[38:41]
	v_mfma_f32_16x16x32_bf16 v[34:37], v[106:109], v[184:187], v[34:37]
	v_mfma_f32_16x16x32_bf16 v[20:23], v[98:101], v[228:231], v[20:23]
	v_mfma_f32_16x16x32_bf16 v[16:19], v[106:109], v[228:231], v[16:19]
	v_mfma_f32_16x16x32_bf16 v[4:7], v[98:101], v[236:239], v[4:7]
	v_mfma_f32_16x16x32_bf16 v[0:3], v[106:109], v[236:239], v[0:3]
	v_mfma_f32_16x16x32_bf16 v[54:57], v[102:105], v[180:183], v[54:57]
	v_mfma_f32_16x16x32_bf16 v[50:53], v[110:113], v[180:183], v[50:53]
	v_mfma_f32_16x16x32_bf16 v[38:41], v[102:105], v[224:227], v[38:41]
	v_mfma_f32_16x16x32_bf16 v[34:37], v[110:113], v[224:227], v[34:37]
	v_mfma_f32_16x16x32_bf16 v[20:23], v[102:105], v[232:235], v[20:23]
	v_mfma_f32_16x16x32_bf16 v[16:19], v[110:113], v[232:235], v[16:19]
	v_mfma_f32_16x16x32_bf16 v[4:7], v[102:105], v[240:243], v[4:7]
	v_mfma_f32_16x16x32_bf16 v[0:3], v[110:113], v[240:243], v[0:3]
	s_setprio 0
	s_barrier
	s_add_u32 s42, s42, 0x100
	s_addc_u32 s43, s43, 0
	s_add_u32 s48, s48, 0x100
	s_addc_u32 s49, s49, 0
	s_cmp_ge_i32 s84, s21
	s_mov_b32 s44, s84
	s_cbranch_scc0 .LBB0_411

.Lhalf_B:
	s_add_i32 s84, s44, 2
	s_add_u32 s10, s42, 0x80
	s_addc_u32 s45, s43, 0
	s_add_i32 s52, 0, 0x10000
	s_cmp_eq_u32 s30, s44
	s_cselect_b32 s45, s81, s45
	s_cselect_b32 s44, s80, s10
	v_add_u32_e32 v32, s52, v216
	s_cselect_b32 s91, s83, s49
	s_cselect_b32 s90, s82, s48
	s_add_i32 s10, 0, 0x14000
	ds_read_b128 v[74:77], v32
	ds_read_b128 v[78:81], v32 offset:1024
	ds_read_b128 v[90:93], v32 offset:2048
	ds_read_b128 v[94:97], v32 offset:3072
	v_add_u32_e32 v32, s10, v216
	ds_read_b128 v[98:101], v32
	ds_read_b128 v[102:105], v32 offset:1024
	ds_read_b128 v[106:109], v32 offset:2048
	ds_read_b128 v[110:113], v32 offset:3072
	v_lshl_add_u64 v[188:189], s[42:43], 0, v[176:177]
	s_add_i32 m0, s3, 0xc000
	ds_read_b128 v[162:165], v218
	ds_read_b128 v[180:183], v218 offset:1024
	ds_read_b128 v[184:187], v218 offset:2048
	ds_read_b128 v[224:227], v218 offset:3072
	ds_read_b128 v[228:231], v218 offset:4096
	ds_read_b128 v[232:235], v218 offset:5120
	ds_read_b128 v[236:239], v218 offset:6144
	ds_read_b128 v[240:243], v218 offset:7168
	global_load_lds_dwordx4 v[188:189], off
	v_lshl_add_u64 v[188:189], s[42:43], 0, v[178:179]
	s_add_i32 m0, s3, 0xe000
	s_nop 0
	global_load_lds_dwordx4 v[188:189], off
	s_waitcnt vmcnt(8)
	s_waitcnt lgkmcnt(0)
	s_barrier
	s_setprio 1
	s_waitcnt lgkmcnt(0)
	v_mfma_f32_16x16x32_bf16 v[154:157], v[74:77], v[162:165], v[154:157]
	v_mfma_f32_16x16x32_bf16 v[158:161], v[90:93], v[162:165], v[158:161]
	v_mfma_f32_16x16x32_bf16 v[142:145], v[74:77], v[184:187], v[142:145]
	v_mfma_f32_16x16x32_bf16 v[138:141], v[90:93], v[184:187], v[138:141]
	v_mfma_f32_16x16x32_bf16 v[126:129], v[74:77], v[228:231], v[126:129]
	v_mfma_f32_16x16x32_bf16 v[122:125], v[90:93], v[228:231], v[122:125]
	v_mfma_f32_16x16x32_bf16 v[86:89], v[74:77], v[236:239], v[86:89]
	v_mfma_f32_16x16x32_bf16 v[82:85], v[90:93], v[236:239], v[82:85]
	v_mfma_f32_16x16x32_bf16 v[154:157], v[78:81], v[180:183], v[154:157]
	v_mfma_f32_16x16x32_bf16 v[158:161], v[94:97], v[180:183], v[158:161]
	v_mfma_f32_16x16x32_bf16 v[142:145], v[78:81], v[224:227], v[142:145]
	v_mfma_f32_16x16x32_bf16 v[138:141], v[94:97], v[224:227], v[138:141]
	v_mfma_f32_16x16x32_bf16 v[126:129], v[78:81], v[232:235], v[126:129]
	v_mfma_f32_16x16x32_bf16 v[122:125], v[94:97], v[232:235], v[122:125]
	v_mfma_f32_16x16x32_bf16 v[86:89], v[78:81], v[240:243], v[86:89]
	v_mfma_f32_16x16x32_bf16 v[82:85], v[94:97], v[240:243], v[82:85]
	s_setprio 0
	s_setprio 1
	v_mfma_f32_16x16x32_bf16 v[150:153], v[98:101], v[162:165], v[150:153]
	v_mfma_f32_16x16x32_bf16 v[146:149], v[106:109], v[162:165], v[146:149]
	v_mfma_f32_16x16x32_bf16 v[134:137], v[98:101], v[184:187], v[134:137]
	v_mfma_f32_16x16x32_bf16 v[130:133], v[106:109], v[184:187], v[130:133]
	v_mfma_f32_16x16x32_bf16 v[118:121], v[98:101], v[228:231], v[118:121]
	v_mfma_f32_16x16x32_bf16 v[114:117], v[106:109], v[228:231], v[114:117]
	v_mfma_f32_16x16x32_bf16 v[70:73], v[98:101], v[236:239], v[70:73]
	v_mfma_f32_16x16x32_bf16 v[66:69], v[106:109], v[236:239], v[66:69]
	v_mfma_f32_16x16x32_bf16 v[150:153], v[102:105], v[180:183], v[150:153]
	v_mfma_f32_16x16x32_bf16 v[146:149], v[110:113], v[180:183], v[146:149]
	v_mfma_f32_16x16x32_bf16 v[134:137], v[102:105], v[224:227], v[134:137]
	v_mfma_f32_16x16x32_bf16 v[130:133], v[110:113], v[224:227], v[130:133]
	v_mfma_f32_16x16x32_bf16 v[118:121], v[102:105], v[232:235], v[118:121]
	v_mfma_f32_16x16x32_bf16 v[114:117], v[110:113], v[232:235], v[114:117]
	v_mfma_f32_16x16x32_bf16 v[70:73], v[102:105], v[240:243], v[70:73]
	v_mfma_f32_16x16x32_bf16 v[66:69], v[110:113], v[240:243], v[66:69]
	s_setprio 0
	s_barrier
	s_add_i32 s52, s52, s2
	v_lshl_add_u64 v[188:189], s[90:91], 0, v[170:171]
	s_mov_b32 m0, s52
	global_load_lds_dwordx4 v[188:189], off
	s_add_i32 m0, s52, 0x2000
	v_lshl_add_u64 v[202:203], s[90:91], 0, v[174:175]
	s_add_u32 s90, s90, s0
	s_addc_u32 s91, s91, s1
	s_add_i32 s10, s10, s2
	global_load_lds_dwordx4 v[202:203], off
	v_lshl_add_u64 v[204:205], s[90:91], 0, v[170:171]
	s_mov_b32 m0, s10
	v_lshl_add_u64 v[212:213], s[90:91], 0, v[174:175]
	global_load_lds_dwordx4 v[204:205], off
	s_add_i32 m0, s10, 0x2000
	v_lshl_add_u64 v[244:245], s[44:45], 0, v[168:169]
	global_load_lds_dwordx4 v[212:213], off
	s_mov_b32 m0, s3
	v_lshl_add_u64 v[246:247], s[44:45], 0, v[172:173]
	global_load_lds_dwordx4 v[244:245], off
	s_mov_b32 m0, s7
	s_nop 0
	global_load_lds_dwordx4 v[246:247], off
	s_waitcnt vmcnt(8)
	s_waitcnt lgkmcnt(0)
	s_barrier
	s_setprio 1
	s_waitcnt lgkmcnt(0)
	s_setprio 0
	s_setprio 1
	s_setprio 0
	s_barrier
	s_add_i32 s10, 0, 0x18000
	v_add_u32_e32 v32, s10, v216
	s_add_i32 s52, 0, 0x1c000
	ds_read_b128 v[74:77], v32
	ds_read_b128 v[78:81], v32 offset:1024
	ds_read_b128 v[90:93], v32 offset:2048
	ds_read_b128 v[94:97], v32 offset:3072
	v_add_u32_e32 v32, s52, v216
	ds_read_b128 v[98:101], v32
	ds_read_b128 v[102:105], v32 offset:1024
	ds_read_b128 v[106:109], v32 offset:2048
	ds_read_b128 v[110:113], v32 offset:3072
	s_add_u32 s44, s44, s0
	s_addc_u32 s45, s45, s1
	s_mov_b32 m0, s9
	v_lshl_add_u64 v[248:249], s[44:45], 0, v[168:169]
	ds_read_b128 v[162:165], v218 offset:32768
	ds_read_b128 v[180:183], v218 offset:33792
	ds_read_b128 v[184:187], v218 offset:34816
	ds_read_b128 v[224:227], v218 offset:35840
	ds_read_b128 v[228:231], v218 offset:36864
	ds_read_b128 v[232:235], v218 offset:37888
	ds_read_b128 v[236:239], v218 offset:38912
	ds_read_b128 v[240:243], v218 offset:39936
	global_load_lds_dwordx4 v[248:249], off
	v_lshl_add_u64 v[248:249], s[44:45], 0, v[172:173]
	s_mov_b32 m0, s12
	s_nop 0
	global_load_lds_dwordx4 v[248:249], off
	s_waitcnt vmcnt(8)
	s_waitcnt lgkmcnt(0)
	s_barrier
	s_setprio 1
	s_waitcnt lgkmcnt(0)
	v_mfma_f32_16x16x32_bf16 v[154:157], v[74:77], v[162:165], v[154:157]
	v_mfma_f32_16x16x32_bf16 v[158:161], v[90:93], v[162:165], v[158:161]
	v_mfma_f32_16x16x32_bf16 v[142:145], v[74:77], v[184:187], v[142:145]
	v_mfma_f32_16x16x32_bf16 v[138:141], v[90:93], v[184:187], v[138:141]
	v_mfma_f32_16x16x32_bf16 v[126:129], v[74:77], v[228:231], v[126:129]
	v_mfma_f32_16x16x32_bf16 v[122:125], v[90:93], v[228:231], v[122:125]
	v_mfma_f32_16x16x32_bf16 v[86:89], v[74:77], v[236:239], v[86:89]
	v_mfma_f32_16x16x32_bf16 v[82:85], v[90:93], v[236:239], v[82:85]
	v_mfma_f32_16x16x32_bf16 v[154:157], v[78:81], v[180:183], v[154:157]
	v_mfma_f32_16x16x32_bf16 v[158:161], v[94:97], v[180:183], v[158:161]
	v_mfma_f32_16x16x32_bf16 v[142:145], v[78:81], v[224:227], v[142:145]
	v_mfma_f32_16x16x32_bf16 v[138:141], v[94:97], v[224:227], v[138:141]
	v_mfma_f32_16x16x32_bf16 v[126:129], v[78:81], v[232:235], v[126:129]
	v_mfma_f32_16x16x32_bf16 v[122:125], v[94:97], v[232:235], v[122:125]
	v_mfma_f32_16x16x32_bf16 v[86:89], v[78:81], v[240:243], v[86:89]
	v_mfma_f32_16x16x32_bf16 v[82:85], v[94:97], v[240:243], v[82:85]
	s_setprio 0
	s_setprio 1
	v_mfma_f32_16x16x32_bf16 v[150:153], v[98:101], v[162:165], v[150:153]
	v_mfma_f32_16x16x32_bf16 v[146:149], v[106:109], v[162:165], v[146:149]
	v_mfma_f32_16x16x32_bf16 v[134:137], v[98:101], v[184:187], v[134:137]
	v_mfma_f32_16x16x32_bf16 v[130:133], v[106:109], v[184:187], v[130:133]
	v_mfma_f32_16x16x32_bf16 v[118:121], v[98:101], v[228:231], v[118:121]
	v_mfma_f32_16x16x32_bf16 v[114:117], v[106:109], v[228:231], v[114:117]
	v_mfma_f32_16x16x32_bf16 v[70:73], v[98:101], v[236:239], v[70:73]
	v_mfma_f32_16x16x32_bf16 v[66:69], v[106:109], v[236:239], v[66:69]
	v_mfma_f32_16x16x32_bf16 v[150:153], v[102:105], v[180:183], v[150:153]
	v_mfma_f32_16x16x32_bf16 v[146:149], v[110:113], v[180:183], v[146:149]
	v_mfma_f32_16x16x32_bf16 v[134:137], v[102:105], v[224:227], v[134:137]
	v_mfma_f32_16x16x32_bf16 v[130:133], v[110:113], v[224:227], v[130:133]
	v_mfma_f32_16x16x32_bf16 v[118:121], v[102:105], v[232:235], v[118:121]
	v_mfma_f32_16x16x32_bf16 v[114:117], v[110:113], v[232:235], v[114:117]
	v_mfma_f32_16x16x32_bf16 v[70:73], v[102:105], v[240:243], v[70:73]
	v_mfma_f32_16x16x32_bf16 v[66:69], v[110:113], v[240:243], v[66:69]
	s_setprio 0
	s_barrier
	s_add_i32 s10, s10, s2
	v_lshl_add_u64 v[188:189], v[188:189], 0, s[56:57]
	s_mov_b32 m0, s10
	global_load_lds_dwordx4 v[188:189], off
	v_lshl_add_u64 v[188:189], v[202:203], 0, s[56:57]
	s_add_i32 m0, s10, 0x2000
	s_add_i32 s10, s52, s2
	global_load_lds_dwordx4 v[188:189], off
	v_lshl_add_u64 v[188:189], v[204:205], 0, s[56:57]
	s_mov_b32 m0, s10
	s_nop 0
	global_load_lds_dwordx4 v[188:189], off
	v_lshl_add_u64 v[188:189], v[212:213], 0, s[56:57]
	s_add_i32 m0, s10, 0x2000
	s_nop 0
	global_load_lds_dwordx4 v[188:189], off
	v_lshl_add_u64 v[188:189], v[244:245], 0, s[56:57]
	s_mov_b32 m0, s13
	s_nop 0
	global_load_lds_dwordx4 v[188:189], off
	v_lshl_add_u64 v[188:189], v[246:247], 0, s[56:57]
	s_mov_b32 m0, s17
	s_nop 0
	global_load_lds_dwordx4 v[188:189], off
	s_waitcnt vmcnt(8)
	s_waitcnt lgkmcnt(0)
	s_barrier
	s_setprio 1
	s_waitcnt lgkmcnt(0)
	s_nop 0
	s_setprio 0
	s_setprio 1
	s_setprio 0
	s_barrier
	s_add_u32 s42, s42, 0x100
	s_addc_u32 s43, s43, 0
	s_add_u32 s48, s48, 0x100
	s_addc_u32 s49, s49, 0
	s_cmp_ge_i32 s84, s21
	s_mov_b32 s44, s84
	s_cbranch_scc0 .Lhalf_B
	s_branch .Lpost_B

.LBB0_559:
	s_add_i32 s49, s42, 2
	s_add_u32 vcc_lo, s0, 0x80
	s_addc_u32 s43, s1, 0
	s_add_i32 s10, 0, 0x10000
	s_cmp_eq_u32 s47, s42
	s_cselect_b32 s43, s35, s43
	s_cselect_b32 s42, s34, vcc_lo
	s_cselect_b32 vcc_hi, s29, s45
	s_cselect_b32 vcc_lo, s28, s44
	s_add_i32 s52, 0, 0x14000
	v_add_u32_e32 v86, s10, v172
	v_add_u32_e32 v175, s52, v172
	ds_read_b128 v[66:69], v86
	ds_read_b128 v[70:73], v86 offset:1024
	ds_read_b128 v[82:85], v86 offset:2048
	ds_read_b128 v[86:89], v86 offset:3072
	ds_read_b128 v[146:149], v175
	ds_read_b128 v[162:165], v175 offset:1024
	ds_read_b128 v[168:171], v175 offset:2048
	ds_read_b128 v[176:179], v175 offset:3072
	v_lshl_add_u64 v[188:189], s[0:1], 0, v[158:159]
	s_add_i32 m0, s7, 0xc000
	ds_read_b128 v[180:183], v174
	ds_read_b128 v[184:187], v174 offset:1024
	ds_read_b128 v[216:219], v174 offset:2048
	ds_read_b128 v[224:227], v174 offset:3072
	ds_read_b128 v[228:231], v174 offset:4096
	ds_read_b128 v[232:235], v174 offset:5120
	ds_read_b128 v[236:239], v174 offset:6144
	ds_read_b128 v[240:243], v174 offset:7168
	global_load_lds_dwordx4 v[188:189], off
	v_lshl_add_u64 v[188:189], s[0:1], 0, v[160:161]
	s_add_i32 m0, s7, 0xe000
	s_nop 0
	global_load_lds_dwordx4 v[188:189], off
	s_waitcnt vmcnt(8)
	s_waitcnt lgkmcnt(0)
	s_barrier
	s_setprio 1
	s_waitcnt lgkmcnt(0)
	s_nop 0
	v_mfma_f32_16x16x32_bf16 v[138:141], v[66:69], v[180:183], v[138:141]
	v_mfma_f32_16x16x32_bf16 v[142:145], v[82:85], v[180:183], v[142:145]
	v_mfma_f32_16x16x32_bf16 v[126:129], v[66:69], v[216:219], v[126:129]
	v_mfma_f32_16x16x32_bf16 v[122:125], v[82:85], v[216:219], v[122:125]
	v_mfma_f32_16x16x32_bf16 v[110:113], v[66:69], v[228:231], v[110:113]
	v_mfma_f32_16x16x32_bf16 v[106:109], v[82:85], v[228:231], v[106:109]
	v_mfma_f32_16x16x32_bf16 v[94:97], v[66:69], v[236:239], v[94:97]
	v_mfma_f32_16x16x32_bf16 v[90:93], v[82:85], v[236:239], v[90:93]
	v_mfma_f32_16x16x32_bf16 v[138:141], v[70:73], v[184:187], v[138:141]
	v_mfma_f32_16x16x32_bf16 v[142:145], v[86:89], v[184:187], v[142:145]
	v_mfma_f32_16x16x32_bf16 v[126:129], v[70:73], v[224:227], v[126:129]
	v_mfma_f32_16x16x32_bf16 v[122:125], v[86:89], v[224:227], v[122:125]
	v_mfma_f32_16x16x32_bf16 v[110:113], v[70:73], v[232:235], v[110:113]
	v_mfma_f32_16x16x32_bf16 v[106:109], v[86:89], v[232:235], v[106:109]
	v_mfma_f32_16x16x32_bf16 v[94:97], v[70:73], v[240:243], v[94:97]
	v_mfma_f32_16x16x32_bf16 v[90:93], v[86:89], v[240:243], v[90:93]
	s_setprio 0
	s_setprio 1
	v_mfma_f32_16x16x32_bf16 v[134:137], v[146:149], v[180:183], v[134:137]
	v_mfma_f32_16x16x32_bf16 v[130:133], v[168:171], v[180:183], v[130:133]
	v_mfma_f32_16x16x32_bf16 v[118:121], v[146:149], v[216:219], v[118:121]
	v_mfma_f32_16x16x32_bf16 v[114:117], v[168:171], v[216:219], v[114:117]
	v_mfma_f32_16x16x32_bf16 v[102:105], v[146:149], v[228:231], v[102:105]
	v_mfma_f32_16x16x32_bf16 v[98:101], v[168:171], v[228:231], v[98:101]
	v_mfma_f32_16x16x32_bf16 v[78:81], v[146:149], v[236:239], v[78:81]
	v_mfma_f32_16x16x32_bf16 v[74:77], v[168:171], v[236:239], v[74:77]
	v_mfma_f32_16x16x32_bf16 v[134:137], v[162:165], v[184:187], v[134:137]
	v_mfma_f32_16x16x32_bf16 v[130:133], v[176:179], v[184:187], v[130:133]
	v_mfma_f32_16x16x32_bf16 v[118:121], v[162:165], v[224:227], v[118:121]
	v_mfma_f32_16x16x32_bf16 v[114:117], v[176:179], v[224:227], v[114:117]
	v_mfma_f32_16x16x32_bf16 v[102:105], v[162:165], v[232:235], v[102:105]
	v_mfma_f32_16x16x32_bf16 v[98:101], v[176:179], v[232:235], v[98:101]
	v_mfma_f32_16x16x32_bf16 v[78:81], v[162:165], v[240:243], v[78:81]
	v_mfma_f32_16x16x32_bf16 v[74:77], v[176:179], v[240:243], v[74:77]
	s_setprio 0
	s_barrier
	s_add_i32 s10, s10, s94
	v_lshl_add_u64 v[188:189], vcc, 0, v[32:33]
	s_mov_b32 m0, s10
	ds_read_b128 v[180:183], v174 offset:16384
	ds_read_b128 v[184:187], v174 offset:17408
	ds_read_b128 v[216:219], v174 offset:18432
	ds_read_b128 v[224:227], v174 offset:19456
	ds_read_b128 v[228:231], v174 offset:20480
	ds_read_b128 v[232:235], v174 offset:21504
	ds_read_b128 v[236:239], v174 offset:22528
	ds_read_b128 v[240:243], v174 offset:23552
	global_load_lds_dwordx4 v[188:189], off
	s_add_i32 m0, s10, 0x2000
	v_lshl_add_u64 v[244:245], vcc, 0, v[154:155]
	s_add_u32 vcc_lo, vcc_lo, s96
	s_addc_u32 vcc_hi, vcc_hi, s97
	s_add_i32 s10, s52, s94
	global_load_lds_dwordx4 v[244:245], off
	v_lshl_add_u64 v[246:247], vcc, 0, v[32:33]
	s_mov_b32 m0, s10
	v_lshl_add_u64 v[248:249], vcc, 0, v[154:155]
	global_load_lds_dwordx4 v[246:247], off
	s_add_i32 m0, s10, 0x2000
	v_lshl_add_u64 v[202:203], s[42:43], 0, v[150:151]
	global_load_lds_dwordx4 v[248:249], off
	s_mov_b32 m0, s7
	v_lshl_add_u64 v[212:213], s[42:43], 0, v[152:153]
	global_load_lds_dwordx4 v[202:203], off
	s_mov_b32 m0, s2
	s_nop 0
	global_load_lds_dwordx4 v[212:213], off
	s_waitcnt vmcnt(8)
	s_waitcnt lgkmcnt(0)
	s_barrier
	s_setprio 1
	s_waitcnt lgkmcnt(0)
	v_mfma_f32_16x16x32_bf16 v[62:65], v[66:69], v[180:183], v[62:65]
	v_mfma_f32_16x16x32_bf16 v[58:61], v[82:85], v[180:183], v[58:61]
	v_mfma_f32_16x16x32_bf16 v[46:49], v[66:69], v[216:219], v[46:49]
	v_mfma_f32_16x16x32_bf16 v[42:45], v[82:85], v[216:219], v[42:45]
	v_mfma_f32_16x16x32_bf16 v[28:31], v[66:69], v[228:231], v[28:31]
	v_mfma_f32_16x16x32_bf16 v[24:27], v[82:85], v[228:231], v[24:27]
	v_mfma_f32_16x16x32_bf16 v[12:15], v[66:69], v[236:239], v[12:15]
	v_mfma_f32_16x16x32_bf16 v[8:11], v[82:85], v[236:239], v[8:11]
	v_mfma_f32_16x16x32_bf16 v[62:65], v[70:73], v[184:187], v[62:65]
	v_mfma_f32_16x16x32_bf16 v[58:61], v[86:89], v[184:187], v[58:61]
	v_mfma_f32_16x16x32_bf16 v[46:49], v[70:73], v[224:227], v[46:49]
	v_mfma_f32_16x16x32_bf16 v[42:45], v[86:89], v[224:227], v[42:45]
	v_mfma_f32_16x16x32_bf16 v[28:31], v[70:73], v[232:235], v[28:31]
	v_mfma_f32_16x16x32_bf16 v[24:27], v[86:89], v[232:235], v[24:27]
	v_mfma_f32_16x16x32_bf16 v[12:15], v[70:73], v[240:243], v[12:15]
	v_mfma_f32_16x16x32_bf16 v[8:11], v[86:89], v[240:243], v[8:11]
	s_setprio 0
	s_setprio 1
	v_mfma_f32_16x16x32_bf16 v[54:57], v[146:149], v[180:183], v[54:57]
	v_mfma_f32_16x16x32_bf16 v[50:53], v[168:171], v[180:183], v[50:53]
	v_mfma_f32_16x16x32_bf16 v[38:41], v[146:149], v[216:219], v[38:41]
	v_mfma_f32_16x16x32_bf16 v[34:37], v[168:171], v[216:219], v[34:37]
	v_mfma_f32_16x16x32_bf16 v[20:23], v[146:149], v[228:231], v[20:23]
	v_mfma_f32_16x16x32_bf16 v[16:19], v[168:171], v[228:231], v[16:19]
	v_mfma_f32_16x16x32_bf16 v[4:7], v[146:149], v[236:239], v[4:7]
	v_mfma_f32_16x16x32_bf16 v[0:3], v[168:171], v[236:239], v[0:3]
	v_mfma_f32_16x16x32_bf16 v[54:57], v[162:165], v[184:187], v[54:57]
	v_mfma_f32_16x16x32_bf16 v[50:53], v[176:179], v[184:187], v[50:53]
	v_mfma_f32_16x16x32_bf16 v[38:41], v[162:165], v[224:227], v[38:41]
	v_mfma_f32_16x16x32_bf16 v[34:37], v[176:179], v[224:227], v[34:37]
	v_mfma_f32_16x16x32_bf16 v[20:23], v[162:165], v[232:235], v[20:23]
	v_mfma_f32_16x16x32_bf16 v[16:19], v[176:179], v[232:235], v[16:19]
	v_mfma_f32_16x16x32_bf16 v[4:7], v[162:165], v[240:243], v[4:7]
	v_mfma_f32_16x16x32_bf16 v[0:3], v[176:179], v[240:243], v[0:3]
	s_setprio 0
	s_barrier
	s_add_i32 s10, 0, 0x18000
	s_add_i32 s52, 0, 0x1c000
	v_add_u32_e32 v86, s10, v172
	v_add_u32_e32 v175, s52, v172
	ds_read_b128 v[66:69], v86
	ds_read_b128 v[70:73], v86 offset:1024
	ds_read_b128 v[82:85], v86 offset:2048
	ds_read_b128 v[86:89], v86 offset:3072
	ds_read_b128 v[146:149], v175
	ds_read_b128 v[162:165], v175 offset:1024
	ds_read_b128 v[168:171], v175 offset:2048
	ds_read_b128 v[176:179], v175 offset:3072
	s_add_u32 s42, s42, s96
	s_addc_u32 s43, s43, s97
	s_mov_b32 m0, s3
	v_lshl_add_u64 v[204:205], s[42:43], 0, v[150:151]
	ds_read_b128 v[180:183], v174 offset:32768
	ds_read_b128 v[184:187], v174 offset:33792
	ds_read_b128 v[216:219], v174 offset:34816
	ds_read_b128 v[224:227], v174 offset:35840
	ds_read_b128 v[228:231], v174 offset:36864
	ds_read_b128 v[232:235], v174 offset:37888
	ds_read_b128 v[236:239], v174 offset:38912
	ds_read_b128 v[240:243], v174 offset:39936
	global_load_lds_dwordx4 v[204:205], off
	v_lshl_add_u64 v[204:205], s[42:43], 0, v[152:153]
	s_mov_b32 m0, s17
	s_nop 0
	global_load_lds_dwordx4 v[204:205], off
	s_waitcnt vmcnt(8)
	s_waitcnt lgkmcnt(0)
	s_barrier
	s_setprio 1
	s_waitcnt lgkmcnt(0)
	v_mfma_f32_16x16x32_bf16 v[138:141], v[66:69], v[180:183], v[138:141]
	v_mfma_f32_16x16x32_bf16 v[142:145], v[82:85], v[180:183], v[142:145]
	v_mfma_f32_16x16x32_bf16 v[126:129], v[66:69], v[216:219], v[126:129]
	v_mfma_f32_16x16x32_bf16 v[122:125], v[82:85], v[216:219], v[122:125]
	v_mfma_f32_16x16x32_bf16 v[110:113], v[66:69], v[228:231], v[110:113]
	v_mfma_f32_16x16x32_bf16 v[106:109], v[82:85], v[228:231], v[106:109]
	v_mfma_f32_16x16x32_bf16 v[94:97], v[66:69], v[236:239], v[94:97]
	v_mfma_f32_16x16x32_bf16 v[90:93], v[82:85], v[236:239], v[90:93]
	v_mfma_f32_16x16x32_bf16 v[138:141], v[70:73], v[184:187], v[138:141]
	v_mfma_f32_16x16x32_bf16 v[142:145], v[86:89], v[184:187], v[142:145]
	v_mfma_f32_16x16x32_bf16 v[126:129], v[70:73], v[224:227], v[126:129]
	v_mfma_f32_16x16x32_bf16 v[122:125], v[86:89], v[224:227], v[122:125]
	v_mfma_f32_16x16x32_bf16 v[110:113], v[70:73], v[232:235], v[110:113]
	v_mfma_f32_16x16x32_bf16 v[106:109], v[86:89], v[232:235], v[106:109]
	v_mfma_f32_16x16x32_bf16 v[94:97], v[70:73], v[240:243], v[94:97]
	v_mfma_f32_16x16x32_bf16 v[90:93], v[86:89], v[240:243], v[90:93]
	s_setprio 0
	s_setprio 1
	v_mfma_f32_16x16x32_bf16 v[134:137], v[146:149], v[180:183], v[134:137]
	v_mfma_f32_16x16x32_bf16 v[130:133], v[168:171], v[180:183], v[130:133]
	v_mfma_f32_16x16x32_bf16 v[118:121], v[146:149], v[216:219], v[118:121]
	v_mfma_f32_16x16x32_bf16 v[114:117], v[168:171], v[216:219], v[114:117]
	v_mfma_f32_16x16x32_bf16 v[102:105], v[146:149], v[228:231], v[102:105]
	v_mfma_f32_16x16x32_bf16 v[98:101], v[168:171], v[228:231], v[98:101]
	v_mfma_f32_16x16x32_bf16 v[78:81], v[146:149], v[236:239], v[78:81]
	v_mfma_f32_16x16x32_bf16 v[74:77], v[168:171], v[236:239], v[74:77]
	v_mfma_f32_16x16x32_bf16 v[134:137], v[162:165], v[184:187], v[134:137]
	v_mfma_f32_16x16x32_bf16 v[130:133], v[176:179], v[184:187], v[130:133]
	v_mfma_f32_16x16x32_bf16 v[118:121], v[162:165], v[224:227], v[118:121]
	v_mfma_f32_16x16x32_bf16 v[114:117], v[176:179], v[224:227], v[114:117]
	v_mfma_f32_16x16x32_bf16 v[102:105], v[162:165], v[232:235], v[102:105]
	v_mfma_f32_16x16x32_bf16 v[98:101], v[176:179], v[232:235], v[98:101]
	v_mfma_f32_16x16x32_bf16 v[78:81], v[162:165], v[240:243], v[78:81]
	v_mfma_f32_16x16x32_bf16 v[74:77], v[176:179], v[240:243], v[74:77]
	s_setprio 0
	s_barrier
	s_add_i32 s10, s10, s94
	v_lshl_add_u64 v[188:189], v[188:189], 0, s[56:57]
	s_mov_b32 m0, s10
	ds_read_b128 v[180:183], v174 offset:49152
	ds_read_b128 v[184:187], v174 offset:50176
	ds_read_b128 v[216:219], v174 offset:51200
	ds_read_b128 v[224:227], v174 offset:52224
	ds_read_b128 v[228:231], v174 offset:53248
	ds_read_b128 v[232:235], v174 offset:54272
	ds_read_b128 v[236:239], v174 offset:55296
	ds_read_b128 v[240:243], v174 offset:56320
	global_load_lds_dwordx4 v[188:189], off
	v_lshl_add_u64 v[188:189], v[244:245], 0, s[56:57]
	s_add_i32 m0, s10, 0x2000
	s_add_i32 s10, s52, s94
	global_load_lds_dwordx4 v[188:189], off
	v_lshl_add_u64 v[188:189], v[246:247], 0, s[56:57]
	s_mov_b32 m0, s10
	s_nop 0
	global_load_lds_dwordx4 v[188:189], off
	v_lshl_add_u64 v[188:189], v[248:249], 0, s[56:57]
	s_add_i32 m0, s10, 0x2000
	s_nop 0
	global_load_lds_dwordx4 v[188:189], off
	v_lshl_add_u64 v[188:189], v[202:203], 0, s[56:57]
	s_mov_b32 m0, s13
	s_nop 0
	global_load_lds_dwordx4 v[188:189], off
	v_lshl_add_u64 v[188:189], v[212:213], 0, s[56:57]
	s_mov_b32 m0, s46
	s_nop 0
	global_load_lds_dwordx4 v[188:189], off
	s_waitcnt vmcnt(8)
	s_waitcnt lgkmcnt(0)
	s_barrier
	s_setprio 1
	s_waitcnt lgkmcnt(0)
	s_nop 0
	v_mfma_f32_16x16x32_bf16 v[62:65], v[66:69], v[180:183], v[62:65]
	v_mfma_f32_16x16x32_bf16 v[58:61], v[82:85], v[180:183], v[58:61]
	v_mfma_f32_16x16x32_bf16 v[46:49], v[66:69], v[216:219], v[46:49]
	v_mfma_f32_16x16x32_bf16 v[42:45], v[82:85], v[216:219], v[42:45]
	v_mfma_f32_16x16x32_bf16 v[28:31], v[66:69], v[228:231], v[28:31]
	v_mfma_f32_16x16x32_bf16 v[24:27], v[82:85], v[228:231], v[24:27]
	v_mfma_f32_16x16x32_bf16 v[12:15], v[66:69], v[236:239], v[12:15]
	v_mfma_f32_16x16x32_bf16 v[8:11], v[82:85], v[236:239], v[8:11]
	v_mfma_f32_16x16x32_bf16 v[62:65], v[70:73], v[184:187], v[62:65]
	v_mfma_f32_16x16x32_bf16 v[58:61], v[86:89], v[184:187], v[58:61]
	v_mfma_f32_16x16x32_bf16 v[46:49], v[70:73], v[224:227], v[46:49]
	v_mfma_f32_16x16x32_bf16 v[42:45], v[86:89], v[224:227], v[42:45]
	v_mfma_f32_16x16x32_bf16 v[28:31], v[70:73], v[232:235], v[28:31]
	v_mfma_f32_16x16x32_bf16 v[24:27], v[86:89], v[232:235], v[24:27]
	v_mfma_f32_16x16x32_bf16 v[12:15], v[70:73], v[240:243], v[12:15]
	v_mfma_f32_16x16x32_bf16 v[8:11], v[86:89], v[240:243], v[8:11]
	s_setprio 0
	s_setprio 1
	v_mfma_f32_16x16x32_bf16 v[54:57], v[146:149], v[180:183], v[54:57]
	v_mfma_f32_16x16x32_bf16 v[50:53], v[168:171], v[180:183], v[50:53]
	v_mfma_f32_16x16x32_bf16 v[38:41], v[146:149], v[216:219], v[38:41]
	v_mfma_f32_16x16x32_bf16 v[34:37], v[168:171], v[216:219], v[34:37]
	v_mfma_f32_16x16x32_bf16 v[20:23], v[146:149], v[228:231], v[20:23]
	v_mfma_f32_16x16x32_bf16 v[16:19], v[168:171], v[228:231], v[16:19]
	v_mfma_f32_16x16x32_bf16 v[4:7], v[146:149], v[236:239], v[4:7]
	v_mfma_f32_16x16x32_bf16 v[0:3], v[168:171], v[236:239], v[0:3]
	v_mfma_f32_16x16x32_bf16 v[54:57], v[162:165], v[184:187], v[54:57]
	v_mfma_f32_16x16x32_bf16 v[50:53], v[176:179], v[184:187], v[50:53]
	v_mfma_f32_16x16x32_bf16 v[38:41], v[162:165], v[224:227], v[38:41]
	v_mfma_f32_16x16x32_bf16 v[34:37], v[176:179], v[224:227], v[34:37]
	v_mfma_f32_16x16x32_bf16 v[20:23], v[162:165], v[232:235], v[20:23]
	v_mfma_f32_16x16x32_bf16 v[16:19], v[176:179], v[232:235], v[16:19]
	v_mfma_f32_16x16x32_bf16 v[4:7], v[162:165], v[240:243], v[4:7]
	v_mfma_f32_16x16x32_bf16 v[0:3], v[176:179], v[240:243], v[0:3]
	s_setprio 0
	s_barrier
	s_add_u32 s0, s0, 0x100
	s_addc_u32 s1, s1, 0
	s_add_u32 s44, s44, 0x100
	s_addc_u32 s45, s45, 0
	s_cmp_ge_i32 s49, s20
	s_mov_b32 s42, s49
	s_cbranch_scc0 .LBB0_559
	v_readlane_b32 s52, v252, 10
	v_readlane_b32 s53, v252, 11
